# diff attention DMA issue: SGPR base + 32-bit lane offset, no per-iteration 64-bit VALU pointer adds
# speedup vs baseline: 1.0288x; 1.0037x over previous
.LBB0_788:
	ds_read_b128 v[238:241], v218 offset:0
	ds_read_b128 v[242:245], v219 offset:0
	ds_read_b128 v[246:249], v218 offset:128
	s_add_i32 s36, s57, -2
	s_cmp_ge_u32 s36, s55
	s_cbranch_scc1 .LBB0_790
	s_add_u32 s74, s34, s10
	s_addc_u32 s75, s35, s11
	s_add_u32 s76, s34, s12
	s_addc_u32 s77, s35, s13
	s_add_i32 m0, s53, 0x14000
	s_nop 0
	global_load_lds_dwordx4 v200, s[74:75]
	s_add_i32 m0, s53, 0x14400
	s_nop 0
	global_load_lds_dwordx4 v198, s[74:75]
	s_add_i32 m0, s54, 0x8000
	s_nop 0
	global_load_lds_dwordx4 v196, s[76:77]
	s_add_i32 m0, s54, 0x8380
	s_nop 0
	global_load_lds_dwordx4 v196, s[76:77] offset:128
	s_add_i32 m0, s54, 0x8700
	s_nop 0
	global_load_lds_dwordx4 v196, s[76:77] offset:256
	s_add_i32 m0, s54, 0x8a80
	s_nop 0
	global_load_lds_dwordx4 v196, s[76:77] offset:384

.Ld16a_end0:
	s_waitcnt vmcnt(0)
	s_cmp_gt_u32 s57, s55
	s_cselect_b64 s[36:37], -1, 0
	s_and_b64 vcc, exec, s[36:37]
	s_waitcnt vmcnt(0) lgkmcnt(0)
	s_barrier
	ds_read_b128 v[238:241], v218 offset:16384
	ds_read_b128 v[242:245], v219 offset:16384
	ds_read_b128 v[246:249], v218 offset:16512
	s_cbranch_vccnz .LBB0_798
	s_add_u32 s74, s34, s20
	s_addc_u32 s75, s35, s21
	s_add_u32 s76, s34, s22
	s_addc_u32 s77, s35, s23
	s_add_i32 m0, s53, 0x10000
	s_nop 0
	global_load_lds_dwordx4 v200, s[74:75]
	s_add_i32 m0, s53, 0x10400
	s_nop 0
	global_load_lds_dwordx4 v198, s[74:75]
	s_mov_b32 m0, s54
	s_nop 0
	global_load_lds_dwordx4 v196, s[76:77]
	s_add_i32 m0, s54, 0x380
	s_nop 0
	global_load_lds_dwordx4 v196, s[76:77] offset:128
	s_add_i32 m0, s54, 0x700
	s_nop 0
	global_load_lds_dwordx4 v196, s[76:77] offset:256
	s_add_i32 m0, s54, 0xa80
	s_nop 0
	global_load_lds_dwordx4 v196, s[76:77] offset:384

.LBB0_2408:
	ds_read_b128 v[238:241], v218 offset:0
	ds_read_b128 v[242:245], v219 offset:0
	ds_read_b128 v[246:249], v218 offset:128
	s_add_i32 s40, s61, -2
	s_cmp_ge_u32 s40, s59
	s_cbranch_scc1 .LBB0_2410
	s_add_u32 s74, s38, s14
	s_addc_u32 s75, s39, s15
	s_add_u32 s76, s38, s16
	s_addc_u32 s77, s39, s17
	s_add_i32 m0, s57, 0x14000
	s_nop 0
	global_load_lds_dwordx4 v200, s[74:75]
	s_add_i32 m0, s57, 0x14400
	s_nop 0
	global_load_lds_dwordx4 v198, s[74:75]
	s_add_i32 m0, s58, 0x8000
	s_nop 0
	global_load_lds_dwordx4 v196, s[76:77]
	s_add_i32 m0, s58, 0x8380
	s_nop 0
	global_load_lds_dwordx4 v196, s[76:77] offset:128
	s_add_i32 m0, s58, 0x8700
	s_nop 0
	global_load_lds_dwordx4 v196, s[76:77] offset:256
	s_add_i32 m0, s58, 0x8a80
	s_nop 0
	global_load_lds_dwordx4 v196, s[76:77] offset:384

.Ld16c_end0:
	s_waitcnt vmcnt(0)
	s_cmp_gt_u32 s61, s59
	s_cselect_b64 s[40:41], -1, 0
	s_and_b64 vcc, exec, s[40:41]
	s_waitcnt vmcnt(0) lgkmcnt(0)
	s_barrier
	ds_read_b128 v[238:241], v218 offset:16384
	ds_read_b128 v[242:245], v219 offset:16384
	ds_read_b128 v[246:249], v218 offset:16512
	s_cbranch_vccnz .LBB0_2418
	s_add_u32 s74, s38, s24
	s_addc_u32 s75, s39, s25
	s_add_u32 s76, s38, s26
	s_addc_u32 s77, s39, s27
	s_add_i32 m0, s57, 0x10000
	s_nop 0
	global_load_lds_dwordx4 v200, s[74:75]
	s_add_i32 m0, s57, 0x10400
	s_nop 0
	global_load_lds_dwordx4 v198, s[74:75]
	s_mov_b32 m0, s58
	s_nop 0
	global_load_lds_dwordx4 v196, s[76:77]
	s_add_i32 m0, s58, 0x380
	s_nop 0
	global_load_lds_dwordx4 v196, s[76:77] offset:128
	s_add_i32 m0, s58, 0x700
	s_nop 0
	global_load_lds_dwordx4 v196, s[76:77] offset:256
	s_add_i32 m0, s58, 0xa80
	s_nop 0
	global_load_lds_dwordx4 v196, s[76:77] offset:384
